# S3 + split-K exchange read-back de-serialised: the 18 (GQA-QKV) / 16 (FFN-up L3) sc1 buffer loads issued in batches into dead fragment registers with one wait per batch
# speedup vs baseline: 1.0014x; 1.0014x over previous
; #define PG8_BAR __builtin_amdgcn_s_barrier()
; #define PG8_BAR __builtin_amdgcn_s_barrier()
; template <class Epi, class Sched>
; __device__ __forceinline__ void gemm_phase_strip(PG8_LAS unsigned char* lds, PG8_LAS unsigned char* slds, PG8_LAS unsigned char* pf, const Gemm g, const Sched& S, const Epi& E, int wv) {
;     ...
;                 PG8_BAR;
; #pragma unroll
;                 for (int j = 0; j < 16; ++j) acc[0][j >> 3][(j >> 1) & 3][j & 1] += __builtin_bit_cast(f32x4, __builtin_amdgcn_raw_buffer_load_b128(rr, vo, j * 8192, 16));
;                 accS[0] += __builtin_bit_cast(f32x4, __builtin_amdgcn_raw_buffer_load_b128(rr, vo, 16 * 8192, 16)); accS[1] += __builtin_bit_cast(f32x4, __builtin_amdgcn_raw_buffer_load_b128(rr, vo, 17 * 8192, 16));
;                 aim = 1; flip = kh;
.LBB0_268:
	s_or_b64 exec, exec, s[2:3]
	s_mul_hi_i32 s2, s1, 0x24000
	s_mul_i32 s1, s1, 0x24000
	s_add_u32 s68, s65, s1
	s_addc_u32 s1, s62, s2
	s_and_b32 s69, s1, 0xffff
	s_barrier
	buffer_load_dwordx4 v[130:133], v128, s[68:71], 0 offen sc1
	s_mov_b32 s1, 0x2000
	buffer_load_dwordx4 v[152:155], v128, s[68:71], s1 offen sc1
	s_mov_b32 s1, 0x4000
	buffer_load_dwordx4 v[156:159], v128, s[68:71], s1 offen sc1
	s_mov_b32 s1, 0x6000
	buffer_load_dwordx4 v[162:165], v128, s[68:71], s1 offen sc1
	s_mov_b32 s1, 0x8000
	buffer_load_dwordx4 v[166:169], v128, s[68:71], s1 offen sc1
	s_mov_b32 s1, 0xa000
	buffer_load_dwordx4 v[170:173], v128, s[68:71], s1 offen sc1
	s_mov_b32 s1, 0xc000
	buffer_load_dwordx4 v[178:181], v128, s[68:71], s1 offen sc1
	s_mov_b32 s1, 0xe000
	buffer_load_dwordx4 v[182:185], v128, s[68:71], s1 offen sc1
	s_mov_b32 s1, 0x10000
	buffer_load_dwordx4 v[186:189], v128, s[68:71], s1 offen sc1
	s_waitcnt vmcnt(0)
	v_pk_add_f32 v[150:151], v[150:151], v[132:133]
	v_pk_add_f32 v[148:149], v[148:149], v[130:131]
	v_pk_add_f32 v[146:147], v[146:147], v[154:155]
	v_pk_add_f32 v[144:145], v[144:145], v[152:153]
	v_pk_add_f32 v[118:119], v[118:119], v[158:159]
	v_pk_add_f32 v[116:117], v[116:117], v[156:157]
	v_pk_add_f32 v[114:115], v[114:115], v[164:165]
	v_pk_add_f32 v[112:113], v[112:113], v[162:163]
	v_pk_add_f32 v[102:103], v[102:103], v[168:169]
	v_pk_add_f32 v[100:101], v[100:101], v[166:167]
	v_pk_add_f32 v[98:99], v[98:99], v[172:173]
	v_pk_add_f32 v[96:97], v[96:97], v[170:171]
	v_pk_add_f32 v[86:87], v[86:87], v[180:181]
	v_pk_add_f32 v[84:85], v[84:85], v[178:179]
	v_pk_add_f32 v[82:83], v[82:83], v[184:185]
	v_pk_add_f32 v[80:81], v[80:81], v[182:183]
	v_pk_add_f32 v[126:127], v[126:127], v[188:189]
	v_pk_add_f32 v[124:125], v[124:125], v[186:187]
	s_mov_b32 s1, 0x12000
	buffer_load_dwordx4 v[130:133], v128, s[68:71], s1 offen sc1
	s_mov_b32 s1, 0x14000
	buffer_load_dwordx4 v[152:155], v128, s[68:71], s1 offen sc1
	s_mov_b32 s1, 0x16000
	buffer_load_dwordx4 v[156:159], v128, s[68:71], s1 offen sc1
	s_mov_b32 s1, 0x18000
	buffer_load_dwordx4 v[162:165], v128, s[68:71], s1 offen sc1
	s_mov_b32 s1, 0x1a000
	buffer_load_dwordx4 v[166:169], v128, s[68:71], s1 offen sc1
	s_mov_b32 s1, 0x1c000
	buffer_load_dwordx4 v[170:173], v128, s[68:71], s1 offen sc1
	s_mov_b32 s1, 0x1e000
	buffer_load_dwordx4 v[178:181], v128, s[68:71], s1 offen sc1
	buffer_load_dwordx4 v[182:185], v128, s[68:71], s71 offen sc1
	s_mov_b32 s1, 0x22000
	buffer_load_dwordx4 v[186:189], v128, s[68:71], s1 offen sc1
	s_waitcnt vmcnt(0)
	v_pk_add_f32 v[122:123], v[122:123], v[132:133]
	v_pk_add_f32 v[120:121], v[120:121], v[130:131]
	v_pk_add_f32 v[110:111], v[110:111], v[154:155]
	v_pk_add_f32 v[108:109], v[108:109], v[152:153]
	v_pk_add_f32 v[106:107], v[106:107], v[158:159]
	v_pk_add_f32 v[104:105], v[104:105], v[156:157]
	v_pk_add_f32 v[94:95], v[94:95], v[164:165]
	v_pk_add_f32 v[92:93], v[92:93], v[162:163]
	v_pk_add_f32 v[90:91], v[90:91], v[168:169]
	v_pk_add_f32 v[88:89], v[88:89], v[166:167]
	v_pk_add_f32 v[78:79], v[78:79], v[172:173]
	v_pk_add_f32 v[76:77], v[76:77], v[170:171]
	v_pk_add_f32 v[74:75], v[74:75], v[180:181]
	v_pk_add_f32 v[72:73], v[72:73], v[178:179]
	v_pk_add_f32 v[4:5], v[4:5], v[182:183]
	v_pk_add_f32 v[6:7], v[6:7], v[184:185]
	v_pk_add_f32 v[2:3], v[2:3], v[188:189]
	v_pk_add_f32 v[0:1], v[0:1], v[186:187]
	s_mov_b32 s1, s91
	s_branch .LBB0_270

; #define PG8_BAR __builtin_amdgcn_s_barrier()
; #define PG8_BAR __builtin_amdgcn_s_barrier()
; template <class Epi, class Sched, bool ALIGN_EPI = false, bool SP2 = false>
; __device__ __forceinline__ void gemm_phase(PG8_LAS unsigned char* lds, PG8_LAS unsigned char* pf, const Gemm g, const Sched& S, const Epi& E, int wv) {
;     ...
;                 PG8_BAR;
; #pragma unroll
;                 for (int j = 0; j < 16; ++j) acc[0][j >> 3][(j >> 1) & 3][j & 1] += __builtin_bit_cast(f32x4, __builtin_amdgcn_raw_buffer_load_b128(rr, vo, j * 8192, 16));
;                 aim = 1; flip = kh;
.LBB0_1471:
	s_or_b64 exec, exec, s[36:37]
	s_ashr_i32 s29, s28, 31
	s_lshl_b64 s[20:21], s[28:29], 17
	s_add_u32 s36, s85, s20
	s_addc_u32 s15, s86, s21
	s_and_b32 s37, s15, 0xffff
	s_mov_b32 s38, s71
	s_mov_b32 s39, s71
	s_barrier
	buffer_load_dwordx4 v[130:133], v128, s[36:39], 0 offen sc1
	s_mov_b32 s15, 0x2000
	buffer_load_dwordx4 v[136:139], v128, s[36:39], s15 offen sc1
	s_mov_b32 s15, 0x4000
	buffer_load_dwordx4 v[140:143], v128, s[36:39], s15 offen sc1
	s_mov_b32 s15, 0x6000
	buffer_load_dwordx4 v[164:167], v128, s[36:39], s15 offen sc1
	s_mov_b32 s15, 0x8000
	buffer_load_dwordx4 v[168:171], v128, s[36:39], s15 offen sc1
	s_mov_b32 s15, 0xa000
	buffer_load_dwordx4 v[172:175], v128, s[36:39], s15 offen sc1
	s_mov_b32 s15, 0xc000
	buffer_load_dwordx4 v[176:179], v128, s[36:39], s15 offen sc1
	s_mov_b32 s15, 0xe000
	buffer_load_dwordx4 v[180:183], v128, s[36:39], s15 offen sc1
	s_mov_b32 s15, 0x10000
	buffer_load_dwordx4 v[184:187], v128, s[36:39], s15 offen sc1
	s_mov_b32 s15, 0x12000
	buffer_load_dwordx4 v[188:191], v128, s[36:39], s15 offen sc1
	s_mov_b32 s15, 0x14000
	buffer_load_dwordx4 v[192:195], v128, s[36:39], s15 offen sc1
	s_mov_b32 s15, 0x16000
	buffer_load_dwordx4 v[196:199], v128, s[36:39], s15 offen sc1
	s_mov_b32 s15, 0x18000
	buffer_load_dwordx4 v[200:203], v128, s[36:39], s15 offen sc1
	s_mov_b32 s15, 0x1a000
	buffer_load_dwordx4 v[204:207], v128, s[36:39], s15 offen sc1
	s_mov_b32 s15, 0x1c000
	buffer_load_dwordx4 v[214:217], v128, s[36:39], s15 offen sc1
	s_mov_b32 s15, 0x1e000
	buffer_load_dwordx4 v[218:221], v128, s[36:39], s15 offen sc1
	s_waitcnt vmcnt(0)
	v_pk_add_f32 v[126:127], v[126:127], v[132:133]
	v_pk_add_f32 v[124:125], v[124:125], v[130:131]
	v_pk_add_f32 v[122:123], v[122:123], v[138:139]
	v_pk_add_f32 v[120:121], v[120:121], v[136:137]
	v_pk_add_f32 v[110:111], v[110:111], v[142:143]
	v_pk_add_f32 v[108:109], v[108:109], v[140:141]
	v_pk_add_f32 v[106:107], v[106:107], v[166:167]
	v_pk_add_f32 v[104:105], v[104:105], v[164:165]
	v_pk_add_f32 v[94:95], v[94:95], v[170:171]
	v_pk_add_f32 v[92:93], v[92:93], v[168:169]
	v_pk_add_f32 v[90:91], v[90:91], v[174:175]
	v_pk_add_f32 v[88:89], v[88:89], v[172:173]
	v_pk_add_f32 v[78:79], v[78:79], v[178:179]
	v_pk_add_f32 v[76:77], v[76:77], v[176:177]
	v_pk_add_f32 v[74:75], v[74:75], v[182:183]
	v_pk_add_f32 v[72:73], v[72:73], v[180:181]
	v_pk_add_f32 v[118:119], v[118:119], v[186:187]
	v_pk_add_f32 v[116:117], v[116:117], v[184:185]
	v_pk_add_f32 v[114:115], v[114:115], v[190:191]
	v_pk_add_f32 v[112:113], v[112:113], v[188:189]
	v_pk_add_f32 v[102:103], v[102:103], v[194:195]
	v_pk_add_f32 v[100:101], v[100:101], v[192:193]
	v_pk_add_f32 v[98:99], v[98:99], v[198:199]
	v_pk_add_f32 v[96:97], v[96:97], v[196:197]
	v_pk_add_f32 v[86:87], v[86:87], v[202:203]
	v_pk_add_f32 v[84:85], v[84:85], v[200:201]
	v_pk_add_f32 v[82:83], v[82:83], v[206:207]
	v_pk_add_f32 v[80:81], v[80:81], v[204:205]
	v_pk_add_f32 v[68:69], v[68:69], v[214:215]
	v_pk_add_f32 v[70:71], v[70:71], v[216:217]
	v_pk_add_f32 v[66:67], v[66:67], v[220:221]
	v_pk_add_f32 v[64:65], v[64:65], v[218:219]
	s_branch .LBB0_1473
